# sample residual GEMM tail keeps three K-slabs in flight (ring of four) and reads LDS fragments before issuing the next DMA
# baseline (speedup 1.0000x reference)
.LBB0_964:
	v_readlane_b32 s2, v254, 1
	s_waitcnt lgkmcnt(0)
	s_and_b64 s[0:1], s[16:17], exec
	v_readlane_b32 s3, v254, 2
	s_load_dwordx2 s[0:1], s[2:3], 0x118
	v_readlane_b32 s21, v254, 0
	s_cselect_b32 s20, 2, 3
	s_waitcnt lgkmcnt(0)
	s_mov_b32 s26, s0
	s_mov_b64 s[0:1], s[2:3]
	s_cmp_gt_u32 s21, 63
	v_mbcnt_lo_u32_b32 v4, -1, 0
	v_mbcnt_hi_u32_b32 v4, -1, v4
	s_cbranch_scc1 .LBB0_977
	s_and_b64 s[2:3], s[14:15], exec
	s_cselect_b32 s2, 1, s20
	s_load_dwordx2 s[10:11], s[0:1], 0x110
	v_readlane_b32 s0, v254, 51
	s_add_i32 s2, s2, s0
	s_lshl_b32 s24, s2, 13
	s_and_b64 s[0:1], s[8:9], exec
	s_movk_i32 s0, 0x400
	s_cselect_b32 s0, 0xb00, s0
	s_waitcnt lgkmcnt(0)
	s_add_u32 s2, s10, 0x7800000
	s_addc_u32 s3, s11, 0
	s_lshl_b64 s[4:5], s[24:25], 2
	s_add_u32 s1, s10, s4
	s_addc_u32 s4, s11, s5
	s_add_u32 s6, s1, 0x1df87000
	s_addc_u32 s7, s4, 0
	s_lshr_b32 s27, s0, 7
	s_and_b64 s[4:5], s[14:15], exec
	s_mov_b32 s4, 0x18d00000
	s_cselect_b32 s16, s4, 0xfb00000
	s_mov_b32 s4, 0x500000
	s_cselect_b32 s17, s4, 0xd00000
	s_and_b64 s[4:5], s[8:9], exec
	s_cselect_b32 s17, 0x1a00000, s17
	s_add_u32 s4, s10, s17
	s_addc_u32 s5, s11, 0
	v_readlane_b32 s35, v254, 37
	s_add_u32 s4, s4, s35
	s_addc_u32 s5, s5, 0
	s_add_u32 s18, s10, 0x12900000
	s_addc_u32 s19, s11, 0
	s_add_u32 s16, s10, s16
	s_addc_u32 s24, s11, 0
	s_add_u32 s16, s16, 0x4000000
	s_addc_u32 s24, s24, 0
	s_and_b64 s[8:9], s[8:9], exec
	s_cselect_b32 s8, s18, s16
	v_add_u32_e32 v0, s67, v4
	v_and_b32_e32 v1, 15, v4
	v_and_b32_e32 v2, 48, v4
	v_readlane_b32 s16, v254, 12
	v_lshl_or_b32 v5, v1, 6, v2
	v_lshlrev_b32_e32 v2, 2, v4
	v_or_b32_e32 v25, s16, v1
	v_ashrrev_i32_e32 v1, 31, v0
	v_lshrrev_b32_e32 v1, 26, v1
	v_add_u32_e32 v1, v0, v1
	v_ashrrev_i32_e32 v1, 6, v1
	v_and_b32_e32 v6, 32, v2
	v_lshlrev_b32_e32 v2, 5, v1
	v_and_b32_e32 v8, 32, v2
	v_lshlrev_b32_e32 v2, 4, v0
	v_bfe_i32 v0, v0, 27, 1
	v_lshrrev_b32_e32 v0, 22, v0
	v_add_u32_e32 v0, v2, v0
	v_and_b32_e32 v0, 0xfffffc00, v0
	v_sub_u32_e32 v0, v2, v0
	v_lshrrev_b32_e32 v2, 4, v0
	v_bitop3_b32 v0, v2, v0, 32 bitop3:0x6c
	v_ashrrev_i32_e32 v2, 31, v0
	v_lshrrev_b32_e32 v2, 26, v2
	v_add_u32_e32 v2, v0, v2
	s_cselect_b32 s9, s19, s24
	v_ashrrev_i32_e32 v9, 6, v2
	v_and_b32_e32 v2, 0xc0, v2
	s_lshl_b32 s16, s27, 15
	v_sub_u32_e32 v0, v0, v2
	v_lshlrev_b32_e32 v1, 3, v1
	s_add_i32 s16, s16, 0xfffe8000
	v_ashrrev_i16_sdwa v0, v191, sext(v0) dst_sel:DWORD dst_unused:UNUSED_PAD src0_sel:DWORD src1_sel:BYTE_0
	v_and_b32_e32 v1, 0x7ffffff0, v1
	s_and_b32 s16, s16, 0x18000
	v_bfe_i32 v10, v0, 0, 16
	v_add_u32_e32 v1, v9, v1
	s_xor_b32 s16, s16, 0x10000
	s_add_i32 s27, s27, -3
	v_add_u32_e32 v0, v8, v10
	v_mul_lo_u32 v9, s0, v1
	s_add_u32 s28, s8, 0x100
	v_add_lshl_u32 v2, v0, v9, 1
	s_addc_u32 s29, s9, 0
	s_lshl_b32 s30, s0, 6
	s_lshl_b32 s31, s21, 6
	s_lshl_b32 s34, s26, 6
	v_lshl_add_u64 v[0:1], s[8:9], 0, v[2:3]
	s_add_u32 s8, s10, s35
	s_addc_u32 s9, s11, 0
	s_add_u32 s8, s8, 0x100
	s_addc_u32 s9, s9, 0
	s_add_u32 s35, s8, s17
	v_and_b32_e32 v7, 63, v4
	s_addc_u32 s38, s9, 0
	v_lshl_add_u64 v[20:21], s[4:5], 0, v[2:3]
	v_lshlrev_b32_e32 v2, 2, v7
	v_xad_u32 v30, v5, v6, 0
	s_add_u32 s39, s28, s0
	v_xor_b32_e32 v26, 64, v2
	v_xor_b32_e32 v27, 0x80, v2
	v_lshrrev_b32_e32 v2, 2, v4
	v_add_u32_e32 v31, s16, v30
	s_addc_u32 s40, s29, 0
	s_or_b32 s10, s17, s0
	v_and_b32_e32 v29, 12, v2
	v_add_u32_e32 v2, s84, v31
	v_or_b32_e32 v4, v9, v8
	s_add_u32 s41, s8, s10
	s_mov_b32 s1, s25
	v_lshl_add_u32 v24, v7, 4, 0
	v_cmp_gt_u32_e64 s[4:5], 16, v7
	v_lshl_add_u32 v28, v25, 2, 0
	v_add_lshl_u32 v22, v4, v10, 1
	v_mov_b32_e32 v23, v3
	s_addc_u32 s42, s9, 0
	v_add_u32_e32 v32, s33, v2
	s_branch .LBB0_968

.LBB0_968:
	s_bfe_u32 s8, s31, 0x20006
	s_mul_i32 s8, s30, s8
	s_lshl_b32 s16, s8, 1
	s_add_u32 s8, s28, s16
	s_addc_u32 s9, s29, 0
	s_lshr_b32 s43, s21, 2
	s_mul_i32 s24, s30, s43
	s_lshl_b64 s[18:19], s[24:25], 1
	s_add_u32 s10, s35, s18
	s_addc_u32 s11, s38, s19
	s_add_u32 s16, s39, s16
	s_addc_u32 s17, s40, 0
	s_add_u32 s18, s41, s18
	s_addc_u32 s19, s42, s19
	s_add_u32 s8, s8, 0x80
	s_addc_u32 s9, s9, 0
	s_add_u32 s10, s10, 0x80
	s_addc_u32 s11, s11, 0
	s_add_u32 s16, s16, 0x80
	s_addc_u32 s17, s17, 0
	s_add_u32 s18, s18, 0x80
	s_addc_u32 s19, s19, 0
	s_lshl_b32 s24, s21, 6
	s_and_b32 s44, s24, 0xc0
	s_mul_i32 s24, s44, s0
	s_lshl_b32 s24, s24, 1
	s_lshl_b32 s45, s43, 6
	s_mov_b32 m0, s57
	s_waitcnt lgkmcnt(0)
	v_lshl_add_u64 v[4:5], v[0:1], 0, s[24:25]
	s_mul_i32 s24, s45, s0
	s_waitcnt vmcnt(0)
	v_lshl_add_u64 v[6:7], s[24:25], 1, v[20:21]
	global_load_lds_dwordx4 v[4:5], off
	s_add_i32 m0, s57, 0x2000
	v_lshl_add_u64 v[8:9], v[4:5], 0, s[0:1]
	global_load_lds_dwordx4 v[6:7], off
	s_add_i32 m0, s57, 0x4000
	v_lshl_add_u64 v[10:11], v[6:7], 0, s[0:1]
	global_load_lds_dwordx4 v[8:9], off
	s_add_i32 m0, s57, 0x6000
	v_lshl_add_u64 v[4:5], v[4:5], 0, s[46:47]
	global_load_lds_dwordx4 v[10:11], off
	s_add_i32 m0, s57, 0x8000
	s_mov_b32 s24, 0
	global_load_lds_dwordx4 v[4:5], off
	v_lshl_add_u64 v[42:43], v[4:5], 0, s[46:47]
	v_lshl_add_u64 v[4:5], v[6:7], 0, s[46:47]
	s_add_i32 m0, s57, 0xa000
	s_mov_b32 s48, 0
	global_load_lds_dwordx4 v[4:5], off
	v_lshl_add_u64 v[4:5], v[8:9], 0, s[46:47]
	s_add_i32 m0, s57, 0xc000
	s_nop 0
	global_load_lds_dwordx4 v[4:5], off
	v_lshl_add_u64 v[4:5], v[10:11], 0, s[46:47]
	s_add_i32 m0, s57, 0xe000
	s_nop 0
	global_load_lds_dwordx4 v[4:5], off
	s_add_i32 m0, s57, 0x10000
	v_lshl_add_u64 v[44:45], v[6:7], 0, s[46:47]
	global_load_lds_dwordx4 v[42:43], off
	v_lshl_add_u64 v[44:45], v[44:45], 0, s[46:47]
	s_add_i32 m0, s57, 0x12000
	v_lshl_add_u64 v[42:43], v[8:9], 0, s[46:47]
	global_load_lds_dwordx4 v[44:45], off
	v_lshl_add_u64 v[42:43], v[42:43], 0, s[46:47]
	s_add_i32 m0, s57, 0x14000
	v_lshl_add_u64 v[44:45], v[10:11], 0, s[46:47]
	global_load_lds_dwordx4 v[42:43], off
	v_lshl_add_u64 v[44:45], v[44:45], 0, s[46:47]
	s_add_i32 m0, s57, 0x16000
	s_nop 0
	global_load_lds_dwordx4 v[44:45], off
	v_mov_b32_e32 v4, 0
	v_mov_b32_e32 v5, v4
	v_mov_b32_e32 v6, v4
	v_mov_b32_e32 v7, v4
	v_mov_b32_e32 v8, v4
	v_mov_b32_e32 v9, v4
	v_mov_b32_e32 v10, v4
	v_mov_b32_e32 v11, v4
	v_mov_b32_e32 v12, v4
	v_mov_b32_e32 v13, v4
	v_mov_b32_e32 v14, v4
	v_mov_b32_e32 v15, v4
	v_mov_b32_e32 v16, v4
	v_mov_b32_e32 v17, v4
	v_mov_b32_e32 v18, v4
	v_mov_b32_e32 v19, v4
.LBB0_969:
	s_waitcnt vmcnt(8)
	s_barrier
	s_and_b32 s50, s24, 0x18000
	s_add_i32 s50, s33, s50
	v_add_u32_e32 v2, s50, v30
	v_add_u32_e32 v33, s84, v2
	ds_read_b128 v[34:37], v33
	ds_read_b128 v[38:41], v2 offset:8192
	ds_read_b128 v[50:53], v2 offset:10240
	ds_read_b128 v[54:57], v2 offset:12288
	ds_read_b128 v[58:61], v2 offset:14336
	ds_read_b128 v[46:49], v33 offset:1024
	ds_read_b128 v[62:65], v2 offset:9216
	ds_read_b128 v[66:69], v2 offset:11264
	ds_read_b128 v[70:73], v2 offset:13312
	ds_read_b128 v[74:77], v2 offset:15360
	s_add_i32 s49, s24, 0x18000
	s_and_b32 s49, s49, 0x18000
	s_add_i32 s49, s57, s49
	v_lshl_add_u64 v[78:79], s[8:9], 0, v[22:23]
	s_mov_b32 m0, s49
	v_lshl_add_u64 v[80:81], s[10:11], 0, v[22:23]
	global_load_lds_dwordx4 v[78:79], off
	s_add_i32 m0, s49, 0x2000
	v_lshl_add_u64 v[82:83], s[16:17], 0, v[22:23]
	global_load_lds_dwordx4 v[80:81], off
	s_add_i32 m0, s49, 0x4000
	v_lshl_add_u64 v[84:85], s[18:19], 0, v[22:23]
	global_load_lds_dwordx4 v[82:83], off
	s_add_i32 m0, s49, 0x6000
	s_nop 0
	global_load_lds_dwordx4 v[84:85], off
	s_add_i32 s48, s48, 1
	s_add_i32 s24, s24, 0x8000
	s_add_u32 s8, s8, 0x80
	s_addc_u32 s9, s9, 0
	s_add_u32 s10, s10, 0x80
	s_addc_u32 s11, s11, 0
	s_add_u32 s16, s16, 0x80
	s_addc_u32 s17, s17, 0
	s_add_u32 s18, s18, 0x80
	s_addc_u32 s19, s19, 0
	s_waitcnt lgkmcnt(8)
	v_mfma_f32_16x16x32_bf16 v[4:7], v[38:41], v[34:37], v[4:7]
	s_waitcnt lgkmcnt(7)
	v_mfma_f32_16x16x32_bf16 v[8:11], v[50:53], v[34:37], v[8:11]
	s_waitcnt lgkmcnt(6)
	v_mfma_f32_16x16x32_bf16 v[12:15], v[54:57], v[34:37], v[12:15]
	s_waitcnt lgkmcnt(5)
	v_mfma_f32_16x16x32_bf16 v[16:19], v[58:61], v[34:37], v[16:19]
	s_waitcnt lgkmcnt(3)
	v_mfma_f32_16x16x32_bf16 v[4:7], v[62:65], v[46:49], v[4:7]
	s_waitcnt lgkmcnt(2)
	v_mfma_f32_16x16x32_bf16 v[8:11], v[66:69], v[46:49], v[8:11]
	s_waitcnt lgkmcnt(1)
	v_mfma_f32_16x16x32_bf16 v[12:15], v[70:73], v[46:49], v[12:15]
	s_cmp_eq_u32 s27, s48
	s_waitcnt lgkmcnt(0)
	v_mfma_f32_16x16x32_bf16 v[16:19], v[74:77], v[46:49], v[16:19]
	s_cbranch_scc0 .LBB0_969
	s_lshl_b32 s8, s27, 15
	s_and_b32 s8, s8, 0x18000
	s_add_i32 s8, s33, s8
	v_add_u32_e32 v2, s8, v30
	s_waitcnt vmcnt(8)
	s_barrier
	v_add_u32_e32 v33, s84, v2
	ds_read_b128 v[34:37], v33
	ds_read_b128 v[38:41], v2 offset:8192
	ds_read_b128 v[50:53], v2 offset:10240
	ds_read_b128 v[54:57], v2 offset:12288
	ds_read_b128 v[58:61], v2 offset:14336
	ds_read_b128 v[46:49], v33 offset:1024
	ds_read_b128 v[62:65], v2 offset:9216
	ds_read_b128 v[66:69], v2 offset:11264
	ds_read_b128 v[70:73], v2 offset:13312
	ds_read_b128 v[74:77], v2 offset:15360
	s_waitcnt lgkmcnt(8)
	v_mfma_f32_16x16x32_bf16 v[4:7], v[38:41], v[34:37], v[4:7]
	s_waitcnt lgkmcnt(7)
	v_mfma_f32_16x16x32_bf16 v[8:11], v[50:53], v[34:37], v[8:11]
	s_waitcnt lgkmcnt(6)
	v_mfma_f32_16x16x32_bf16 v[12:15], v[54:57], v[34:37], v[12:15]
	s_waitcnt lgkmcnt(5)
	v_mfma_f32_16x16x32_bf16 v[16:19], v[58:61], v[34:37], v[16:19]
	s_waitcnt lgkmcnt(3)
	v_mfma_f32_16x16x32_bf16 v[4:7], v[62:65], v[46:49], v[4:7]
	s_waitcnt lgkmcnt(2)
	v_mfma_f32_16x16x32_bf16 v[8:11], v[66:69], v[46:49], v[8:11]
	s_waitcnt lgkmcnt(1)
	v_mfma_f32_16x16x32_bf16 v[12:15], v[70:73], v[46:49], v[12:15]
	s_waitcnt lgkmcnt(0)
	v_mfma_f32_16x16x32_bf16 v[16:19], v[74:77], v[46:49], v[16:19]
	s_add_i32 s8, s27, 1
	s_lshl_b32 s8, s8, 15
	s_and_b32 s8, s8, 0x18000
	s_add_i32 s8, s33, s8
	v_add_u32_e32 v2, s8, v30
	s_waitcnt vmcnt(4)
	s_barrier
	v_add_u32_e32 v33, s84, v2
	ds_read_b128 v[34:37], v33
	ds_read_b128 v[38:41], v2 offset:8192
	ds_read_b128 v[50:53], v2 offset:10240
	ds_read_b128 v[54:57], v2 offset:12288
	ds_read_b128 v[58:61], v2 offset:14336
	ds_read_b128 v[46:49], v33 offset:1024
	ds_read_b128 v[62:65], v2 offset:9216
	ds_read_b128 v[66:69], v2 offset:11264
	ds_read_b128 v[70:73], v2 offset:13312
	ds_read_b128 v[74:77], v2 offset:15360
	v_readlane_b32 s8, v254, 13
	v_readlane_b32 s9, v254, 14
	s_waitcnt lgkmcnt(8)
	v_mfma_f32_16x16x32_bf16 v[4:7], v[38:41], v[34:37], v[4:7]
	s_waitcnt lgkmcnt(7)
	v_mfma_f32_16x16x32_bf16 v[8:11], v[50:53], v[34:37], v[8:11]
	s_waitcnt lgkmcnt(6)
	v_mfma_f32_16x16x32_bf16 v[12:15], v[54:57], v[34:37], v[12:15]
	s_waitcnt lgkmcnt(5)
	v_mfma_f32_16x16x32_bf16 v[16:19], v[58:61], v[34:37], v[16:19]
	s_waitcnt lgkmcnt(3)
	v_mfma_f32_16x16x32_bf16 v[4:7], v[62:65], v[46:49], v[4:7]
	s_waitcnt lgkmcnt(2)
	v_mfma_f32_16x16x32_bf16 v[8:11], v[66:69], v[46:49], v[8:11]
	s_waitcnt lgkmcnt(1)
	v_mfma_f32_16x16x32_bf16 v[12:15], v[70:73], v[46:49], v[12:15]
	s_waitcnt lgkmcnt(0)
	v_mfma_f32_16x16x32_bf16 v[16:19], v[74:77], v[46:49], v[16:19]
	s_and_b64 vcc, exec, s[8:9]
	s_waitcnt vmcnt(0)
	s_barrier
	v_add_u32_e32 v2, s33, v31
	ds_read_b128 v[34:37], v32
	ds_read_b128 v[38:41], v2 offset:8192
	ds_read_b128 v[50:53], v2 offset:10240
	ds_read_b128 v[54:57], v2 offset:12288
	ds_read_b128 v[58:61], v2 offset:14336
	ds_read_b128 v[46:49], v32 offset:1024
	ds_read_b128 v[62:65], v2 offset:9216
	ds_read_b128 v[66:69], v2 offset:11264
	ds_read_b128 v[70:73], v2 offset:13312
	ds_read_b128 v[74:77], v2 offset:15360
	s_waitcnt lgkmcnt(8)
	v_mfma_f32_16x16x32_bf16 v[4:7], v[38:41], v[34:37], v[4:7]
	s_waitcnt lgkmcnt(7)
	v_mfma_f32_16x16x32_bf16 v[8:11], v[50:53], v[34:37], v[8:11]
	s_waitcnt lgkmcnt(6)
	v_mfma_f32_16x16x32_bf16 v[12:15], v[54:57], v[34:37], v[12:15]
	s_waitcnt lgkmcnt(5)
	v_mfma_f32_16x16x32_bf16 v[16:19], v[58:61], v[34:37], v[16:19]
	s_waitcnt lgkmcnt(3)
	v_mfma_f32_16x16x32_bf16 v[4:7], v[62:65], v[46:49], v[4:7]
	s_waitcnt lgkmcnt(2)
	v_mfma_f32_16x16x32_bf16 v[8:11], v[66:69], v[46:49], v[8:11]
	s_waitcnt lgkmcnt(1)
	v_mfma_f32_16x16x32_bf16 v[12:15], v[70:73], v[46:49], v[12:15]
	s_waitcnt lgkmcnt(0)
	v_mfma_f32_16x16x32_bf16 v[16:19], v[74:77], v[46:49], v[16:19]
	s_nop 1
	s_barrier
	s_cbranch_vccz .LBB0_974
	v_add_u32_e32 v2, s85, v24
	ds_write_b128 v2, v[4:7]
	ds_write_b128 v2, v[8:11] offset:1024
	ds_write_b128 v2, v[12:15] offset:2048
	s_nop 2
	ds_write_b128 v2, v[16:19] offset:3072
	s_and_saveexec_b64 s[8:9], s[4:5]
	ds_write_b32 v28, v3 offset:16384
	s_or_b64 exec, exec, s[8:9]
